# ResNorm epilogue: row-sum flag published before the norm/adaLN vector loads are issued (they no longer delay the flag)
# speedup vs baseline: 1.0273x; 1.0009x over previous
.Lrn_nw_7:
	s_or_b64 exec, exec, s[0:1]
	s_waitcnt lgkmcnt(0)
	v_mov_b64_e32 v[180:181], 0x240
	v_mov_b64_e32 v[182:183], 0x23f
	v_mov_b64_e32 v[186:187], 0x41f
	v_mov_b64_e32 v[188:189], 0xc0
	v_mov_b64_e32 v[190:191], 0xbf
	s_waitcnt lgkmcnt(0)
	s_barrier
	v_and_b32_e32 v242, 31, v192
	s_waitcnt lgkmcnt(0)
	v_lshl_or_b32 v161, s34, 5, v242
	v_cmp_gt_u32_e64 s[0:1], 32, v224
	v_lshl_add_u32 v242, s22, 8, v161
	s_and_saveexec_b64 s[36:37], s[0:1]
	s_cbranch_execz .LBB0_914

	v_lshl_add_u32 v243, v161, 4, 0
	ds_read_b128 v[248:251], v243
	v_ashrrev_i32_e32 v243, 31, v242
	s_ashr_i32 s63, s62, 31
	s_waitcnt lgkmcnt(0)
	v_mov_b32_e32 v184, v249
	v_mov_b32_e32 v185, v250
	v_mov_b32_e32 v249, v251
	v_pk_add_f32 v[248:249], v[184:185], v[248:249]
	v_lshl_add_u64 v[250:251], v[242:243], 4, s[60:61]
	v_pk_add_f32 v[248:249], v[248:249], v[248:249] op_sel:[0,1] op_sel_hi:[1,0]
	v_lshl_add_u64 v[250:251], s[62:63], 2, v[250:251]
	global_store_dword v[250:251], v248, off sc1

.LBB0_917:
	s_or_b64 exec, exec, s[36:37]
	v_lshlrev_b32_e32 v193, 2, v210
	global_load_dwordx4 v[128:131], v193, s[58:59]
	global_load_dwordx4 v[136:139], v193, s[58:59] offset:64
	global_load_dwordx4 v[120:123], v193, s[58:59] offset:512
	global_load_dwordx4 v[112:115], v193, s[58:59] offset:576
	s_and_b64 vcc, exec, s[38:39]
	s_cbranch_vccnz .Lmh_nomod_a
	v_readlane_b32 s98, v255, 14
	v_readlane_b32 s99, v255, 15
	s_add_u32 s100, s44, s2
	s_addc_u32 s101, s45, s3
	s_add_u32 s98, s98, s2
	s_addc_u32 s99, s99, s3
	global_load_dwordx4 v[140:143], v193, s[100:101]
	global_load_dwordx4 v[108:111], v193, s[100:101] offset:64
	global_load_dwordx4 v[132:135], v193, s[100:101] offset:512
	global_load_dwordx4 v[100:103], v193, s[100:101] offset:576
	global_load_dwordx4 v[226:229], v193, s[98:99]
	global_load_dwordx4 v[230:233], v193, s[98:99] offset:64
	global_load_dwordx4 v[234:237], v193, s[98:99] offset:512
	global_load_dwordx4 v[238:241], v193, s[98:99] offset:576
.Lmh_nomod_a:
	s_and_b64 vcc, exec, s[38:39]
	s_cbranch_vccnz .Lxs_skip
	global_store_dwordx4 v[208:209], v[156:159], off
	global_store_dwordx4 v[208:209], v[152:155], off offset:64
	global_store_dwordx4 v[208:209], v[148:151], off offset:512
	global_store_dwordx4 v[208:209], v[116:119], off offset:576
	global_store_dwordx4 v[204:205], v[144:147], off
	global_store_dwordx4 v[204:205], v[124:127], off offset:64
	global_store_dwordx4 v[204:205], v[104:107], off offset:512
	global_store_dwordx4 v[204:205], v[92:95], off offset:576
	global_store_dwordx4 v[200:201], v[96:99], off
	global_store_dwordx4 v[200:201], v[88:91], off offset:64
	global_store_dwordx4 v[200:201], v[84:87], off offset:512
	global_store_dwordx4 v[200:201], v[76:79], off offset:576
	global_store_dwordx4 v[196:197], v[80:83], off
	global_store_dwordx4 v[196:197], v[72:75], off offset:64
	global_store_dwordx4 v[196:197], v[68:71], off offset:512
	global_store_dwordx4 v[196:197], v[60:63], off offset:576
	global_store_dwordx4 v[176:177], v[64:67], off
	global_store_dwordx4 v[176:177], v[56:59], off offset:64
	global_store_dwordx4 v[176:177], v[52:55], off offset:512
	global_store_dwordx4 v[176:177], v[44:47], off offset:576
	global_store_dwordx4 v[172:173], v[48:51], off
	global_store_dwordx4 v[172:173], v[40:43], off offset:64
	global_store_dwordx4 v[172:173], v[36:39], off offset:512
	global_store_dwordx4 v[172:173], v[32:35], off offset:576
	global_store_dwordx4 v[168:169], v[28:31], off
	global_store_dwordx4 v[168:169], v[24:27], off offset:64
	global_store_dwordx4 v[168:169], v[20:23], off offset:512
	global_store_dwordx4 v[168:169], v[16:19], off offset:576
	global_store_dwordx4 v[164:165], v[12:15], off
	global_store_dwordx4 v[164:165], v[8:11], off offset:64
	global_store_dwordx4 v[164:165], v[4:7], off offset:512
	global_store_dwordx4 v[164:165], v[0:3], off offset:576
